# FFN-up K-loop: saddr-form LDS-DMA loads (8 fewer 64-bit VALU adds per iteration); all K-loops: first iteration peeled with SrcC=0 instead of zeroing 128 accumulator VGPRs; census loads issued together
# speedup vs baseline: 1.0136x; 1.0065x over previous
; #define PG8_STAGE(bufoff, gbase, voff) do { _Pragma("unroll") for (int _i = 0; _i < 2; ++_i) \
;         __builtin_amdgcn_global_load_lds((const unsigned*)((const char*)(gbase) + (voff)[_i]), (PG8_LAS unsigned*)(lds + (bufoff) + ldsw + _i * 8192), 16, 0, 0); } while (0)
; #define PG8_LDA(dst, b, h) do { _Pragma("unroll") for (int m = 0; m < 4; ++m) _Pragma("unroll") for (int k = 0; k < 2; ++k) dst[m][k] = *(const PG8_LAS bf16x8*)(lds + PG8_SA(b, h) + aoff + m * 2048 + k * 1024); } while (0)
; #define PG8_LDB(dst, b, h) do { _Pragma("unroll") for (int n = 0; n < 2; ++n) _Pragma("unroll") for (int k = 0; k < 2; ++k) dst[n][k] = *(const PG8_LAS bf16x8*)(lds + PG8_SB(b, h) + boff + n * 2048 + k * 1024); } while (0)
; #define PG8_MMA(ai, bj, At, Bt) do { __builtin_amdgcn_s_setprio(1); _Pragma("unroll") for (int m = 0; m < 4; ++m) _Pragma("unroll") for (int n = 0; n < 2; ++n) _Pragma("unroll") for (int k = 0; k < 2; ++k) \
;         acc[ai][bj][m][n] = mma16<Epi::I8>(Bt[n][k], At[m][k], acc[ai][bj][m][n]); __builtin_amdgcn_s_setprio(0); } while (0)
; #define PG8_WAIT_V(n) asm volatile("s_waitcnt vmcnt(" #n ")" ::: "memory")
; #define PG8_WAIT_L(n) asm volatile("s_waitcnt lgkmcnt(" #n ")" ::: "memory")
; #define PG8_BAR __builtin_amdgcn_s_barrier()
; #define PG8_SCHED __builtin_amdgcn_sched_barrier(0)
; template <class Epi, class Sched, bool ALIGN_EPI = false, bool SP2 = false>
; __device__ __forceinline__ void gemm_phase(PG8_LAS unsigned char* lds, const Gemm g, const Sched& S, const Epi& E) {
;     ...
;             PG8_LDB(B0, 0, 0); PG8_LDB(B1, 0, 1); PG8_SCHED; PG8_LDA(At, 0, 0); PG8_STAGE(PG8_SA(1, 1), a1 + hstep, voffA);
;             PG8_WAIT_V(8); PG8_WAIT_L(0); PG8_BAR; PG8_MMA(0, 0, At, B0); PG8_MMA(0, 1, At, B1); PG8_BAR; PG8_SCHED;
;             PG8_LDA(At, 0, 1); PG8_STAGE(PG8_SB(0, 0), b2, voffB); PG8_STAGE(PG8_SB(0, 1), b2 + hstep, voffB); PG8_STAGE(PG8_SA(0, 0), a2, voffA);
;             PG8_WAIT_V(8); PG8_WAIT_L(0); PG8_BAR; PG8_MMA(1, 0, At, B0); PG8_MMA(1, 1, At, B1); PG8_BAR; PG8_SCHED;
.Lpeel80:
	s_add_u32 s8, s0, 0x100
	s_addc_u32 s9, s1, 0
	s_add_i32 vcc_hi, 0, 0x10000
	s_cmp_eq_u32 vcc_lo, 12
	s_cselect_b32 s13, s66, s9
	s_cselect_b32 s12, s67, s8
	s_cselect_b32 s7, s82, s97
	s_cselect_b32 s6, s83, s96
	s_add_i32 s4, 0, 0x14000
	v_add_u32_e32 v38, vcc_hi, v242
	v_add_u32_e32 v158, s4, v242
	ds_read_b128 v[18:21], v38
	ds_read_b128 v[22:25], v38 offset:1024
	ds_read_b128 v[34:37], v38 offset:2048
	ds_read_b128 v[38:41], v38 offset:3072
	ds_read_b128 v[130:133], v158
	ds_read_b128 v[134:137], v158 offset:1024
	ds_read_b128 v[154:157], v158 offset:2048
	ds_read_b128 v[158:161], v158 offset:3072
	s_add_i32 m0, s11, 0xc000
	ds_read_b128 v[162:165], v243
	ds_read_b128 v[166:169], v243 offset:1024
	ds_read_b128 v[170:173], v243 offset:2048
	ds_read_b128 v[174:177], v243 offset:3072
	ds_read_b128 v[178:181], v243 offset:4096
	ds_read_b128 v[182:185], v243 offset:5120
	ds_read_b128 v[186:189], v243 offset:6144
	ds_read_b128 v[190:193], v243 offset:7168
	global_load_lds_dwordx4 v216, s[0:1]
	s_add_i32 m0, s11, 0xe000
	s_nop 0
	global_load_lds_dwordx4 v218, s[0:1]
	s_waitcnt vmcnt(8)
	s_waitcnt lgkmcnt(0)
	s_barrier
	s_setprio 1
	s_waitcnt lgkmcnt(0)
	v_mfma_i32_16x16x64_i8 v[150:153], v[18:21], v[162:165], 0
	v_mfma_i32_16x16x64_i8 v[146:149], v[34:37], v[162:165], 0
	v_mfma_i32_16x16x64_i8 v[118:121], v[18:21], v[170:173], 0
	v_mfma_i32_16x16x64_i8 v[110:113], v[34:37], v[170:173], 0
	v_mfma_i32_16x16x64_i8 v[54:57], v[18:21], v[178:181], 0
	v_mfma_i32_16x16x64_i8 v[30:33], v[34:37], v[178:181], 0
	v_mfma_i32_16x16x64_i8 v[94:97], v[18:21], v[186:189], 0
	v_mfma_i32_16x16x64_i8 v[58:61], v[34:37], v[186:189], 0
	v_mfma_i32_16x16x64_i8 v[150:153], v[22:25], v[166:169], v[150:153]
	v_mfma_i32_16x16x64_i8 v[146:149], v[38:41], v[166:169], v[146:149]
	v_mfma_i32_16x16x64_i8 v[118:121], v[22:25], v[174:177], v[118:121]
	v_mfma_i32_16x16x64_i8 v[110:113], v[38:41], v[174:177], v[110:113]
	v_mfma_i32_16x16x64_i8 v[54:57], v[22:25], v[182:185], v[54:57]
	v_mfma_i32_16x16x64_i8 v[30:33], v[38:41], v[182:185], v[30:33]
	v_mfma_i32_16x16x64_i8 v[94:97], v[22:25], v[190:193], v[94:97]
	v_mfma_i32_16x16x64_i8 v[58:61], v[38:41], v[190:193], v[58:61]
	s_setprio 0
	s_setprio 1
	v_mfma_i32_16x16x64_i8 v[142:145], v[130:133], v[162:165], 0
	v_mfma_i32_16x16x64_i8 v[138:141], v[154:157], v[162:165], 0
	v_mfma_i32_16x16x64_i8 v[102:105], v[130:133], v[170:173], 0
	v_mfma_i32_16x16x64_i8 v[98:101], v[154:157], v[170:173], 0
	v_mfma_i32_16x16x64_i8 v[42:45], v[130:133], v[178:181], 0
	v_mfma_i32_16x16x64_i8 v[26:29], v[154:157], v[178:181], 0
	v_mfma_i32_16x16x64_i8 v[78:81], v[130:133], v[186:189], 0
	v_mfma_i32_16x16x64_i8 v[62:65], v[154:157], v[186:189], 0
	v_mfma_i32_16x16x64_i8 v[142:145], v[134:137], v[166:169], v[142:145]
	v_mfma_i32_16x16x64_i8 v[138:141], v[158:161], v[166:169], v[138:141]
	v_mfma_i32_16x16x64_i8 v[102:105], v[134:137], v[174:177], v[102:105]
	v_mfma_i32_16x16x64_i8 v[98:101], v[158:161], v[174:177], v[98:101]
	v_mfma_i32_16x16x64_i8 v[42:45], v[134:137], v[182:185], v[42:45]
	v_mfma_i32_16x16x64_i8 v[26:29], v[158:161], v[182:185], v[26:29]
	v_mfma_i32_16x16x64_i8 v[78:81], v[134:137], v[190:193], v[78:81]
	v_mfma_i32_16x16x64_i8 v[62:65], v[158:161], v[190:193], v[62:65]
	s_setprio 0
	s_barrier
	s_add_i32 s0, vcc_hi, s69
	v_lshl_add_u64 v[198:199], s[6:7], 0, v[0:1]
	s_mov_b32 m0, s0
	ds_read_b128 v[162:165], v243 offset:16384
	ds_read_b128 v[166:169], v243 offset:17408
	ds_read_b128 v[170:173], v243 offset:18432
	ds_read_b128 v[174:177], v243 offset:19456
	ds_read_b128 v[178:181], v243 offset:20480
	ds_read_b128 v[182:185], v243 offset:21504
	ds_read_b128 v[186:189], v243 offset:22528
	ds_read_b128 v[190:193], v243 offset:23552
	global_load_lds_dwordx4 v[198:199], off
	s_add_i32 m0, s0, 0x2000
	s_add_u32 s0, s6, 0x40000
	v_lshl_add_u64 v[200:201], s[6:7], 0, v[214:215]
	s_addc_u32 s1, s7, 0
	s_add_i32 s4, s4, s69
	global_load_lds_dwordx4 v[200:201], off
	s_mov_b32 m0, s4
	v_lshl_add_u64 v[206:207], s[12:13], 0, v[210:211]
	global_load_lds_dwordx4 v0, s[0:1]
	s_add_i32 m0, s4, 0x2000
	v_lshl_add_u64 v[220:221], s[12:13], 0, v[212:213]
	global_load_lds_dwordx4 v214, s[0:1]
	s_mov_b32 m0, s11
	s_nop 0
	global_load_lds_dwordx4 v[206:207], off
	s_mov_b32 m0, s71
	s_nop 0
	global_load_lds_dwordx4 v[220:221], off
	s_waitcnt vmcnt(8)
	s_waitcnt lgkmcnt(0)
	s_barrier
	s_setprio 1
	s_waitcnt lgkmcnt(0)
	v_mfma_i32_16x16x64_i8 v[106:109], v[18:21], v[162:165], 0
	v_mfma_i32_16x16x64_i8 v[46:49], v[34:37], v[162:165], 0
	v_mfma_i32_16x16x64_i8 v[14:17], v[18:21], v[170:173], 0
	v_mfma_i32_16x16x64_i8 v[6:9], v[34:37], v[170:173], 0
	v_mfma_i32_16x16x64_i8 v[90:93], v[18:21], v[178:181], 0
	v_mfma_i32_16x16x64_i8 v[86:89], v[34:37], v[178:181], 0
	v_mfma_i32_16x16x64_i8 v[18:21], v[18:21], v[186:189], 0
	v_mfma_i32_16x16x64_i8 v[106:109], v[22:25], v[166:169], v[106:109]
	v_mfma_i32_16x16x64_i8 v[46:49], v[38:41], v[166:169], v[46:49]
	v_mfma_i32_16x16x64_i8 v[14:17], v[22:25], v[174:177], v[14:17]
	v_mfma_i32_16x16x64_i8 v[6:9], v[38:41], v[174:177], v[6:9]
	v_mfma_i32_16x16x64_i8 v[90:93], v[22:25], v[182:185], v[90:93]
	v_mfma_i32_16x16x64_i8 v[86:89], v[38:41], v[182:185], v[86:89]
	v_mfma_i32_16x16x64_i8 v[18:21], v[22:25], v[190:193], v[18:21]
	v_mfma_i32_16x16x64_i8 v[22:25], v[34:37], v[186:189], 0
	v_mfma_i32_16x16x64_i8 v[22:25], v[38:41], v[190:193], v[22:25]
	s_setprio 0
	s_setprio 1
	v_mfma_i32_16x16x64_i8 v[38:41], v[154:157], v[162:165], 0
	v_mfma_i32_16x16x64_i8 v[50:53], v[130:133], v[178:181], 0
	v_mfma_i32_16x16x64_i8 v[82:85], v[134:137], v[182:185], v[50:53]
	v_mfma_i32_16x16x64_i8 v[50:53], v[154:157], v[178:181], 0
	v_mfma_i32_16x16x64_i8 v[74:77], v[158:161], v[182:185], v[50:53]
	v_mfma_i32_16x16x64_i8 v[50:53], v[130:133], v[186:189], 0
	v_mfma_i32_16x16x64_i8 v[10:13], v[130:133], v[170:173], 0
	v_mfma_i32_16x16x64_i8 v[2:5], v[154:157], v[170:173], 0
	v_mfma_i32_16x16x64_i8 v[122:125], v[134:137], v[190:193], v[50:53]
	v_mfma_i32_16x16x64_i8 v[50:53], v[154:157], v[186:189], 0
	v_mfma_i32_16x16x64_i8 v[34:37], v[130:133], v[162:165], 0
	v_mfma_i32_16x16x64_i8 v[10:13], v[134:137], v[174:177], v[10:13]
	v_mfma_i32_16x16x64_i8 v[2:5], v[158:161], v[174:177], v[2:5]
	v_mfma_i32_16x16x64_i8 v[70:73], v[158:161], v[190:193], v[50:53]
	v_mfma_i32_16x16x64_i8 v[34:37], v[134:137], v[166:169], v[34:37]
	v_mfma_i32_16x16x64_i8 v[38:41], v[158:161], v[166:169], v[38:41]
	s_setprio 0
	s_barrier
; #define PG8_STAGE(bufoff, gbase, voff) do { _Pragma("unroll") for (int _i = 0; _i < 2; ++_i) \
;         __builtin_amdgcn_global_load_lds((const unsigned*)((const char*)(gbase) + (voff)[_i]), (PG8_LAS unsigned*)(lds + (bufoff) + ldsw + _i * 8192), 16, 0, 0); } while (0)
; #define PG8_LDA(dst, b, h) do { _Pragma("unroll") for (int m = 0; m < 4; ++m) _Pragma("unroll") for (int k = 0; k < 2; ++k) dst[m][k] = *(const PG8_LAS bf16x8*)(lds + PG8_SA(b, h) + aoff + m * 2048 + k * 1024); } while (0)
; #define PG8_LDB(dst, b, h) do { _Pragma("unroll") for (int n = 0; n < 2; ++n) _Pragma("unroll") for (int k = 0; k < 2; ++k) dst[n][k] = *(const PG8_LAS bf16x8*)(lds + PG8_SB(b, h) + boff + n * 2048 + k * 1024); } while (0)
; #define PG8_MMA(ai, bj, At, Bt) do { __builtin_amdgcn_s_setprio(1); _Pragma("unroll") for (int m = 0; m < 4; ++m) _Pragma("unroll") for (int n = 0; n < 2; ++n) _Pragma("unroll") for (int k = 0; k < 2; ++k) \
;         acc[ai][bj][m][n] = mma16<Epi::I8>(Bt[n][k], At[m][k], acc[ai][bj][m][n]); __builtin_amdgcn_s_setprio(0); } while (0)
; #define PG8_WAIT_V(n) asm volatile("s_waitcnt vmcnt(" #n ")" ::: "memory")
; #define PG8_WAIT_L(n) asm volatile("s_waitcnt lgkmcnt(" #n ")" ::: "memory")
; #define PG8_BAR __builtin_amdgcn_s_barrier()
; #define PG8_SCHED __builtin_amdgcn_sched_barrier(0)
; template <class Epi, class Sched, bool ALIGN_EPI = false, bool SP2 = false>
; __device__ __forceinline__ void gemm_phase(PG8_LAS unsigned char* lds, const Gemm g, const Sched& S, const Epi& E) {
;     ...
;         for (int t = 0; t < nt; t += 2) {
;     ...
;             PG8_LDB(B0, 1, 0); PG8_LDB(B1, 1, 1); PG8_SCHED; PG8_LDA(At, 1, 0); PG8_STAGE(PG8_SA(0, 1), a2 + hstep, voffA);
;             PG8_WAIT_V(8); PG8_WAIT_L(0); PG8_BAR; PG8_MMA(0, 0, At, B0); PG8_MMA(0, 1, At, B1); PG8_BAR; PG8_SCHED;
;             PG8_LDA(At, 1, 1); PG8_STAGE(PG8_SB(1, 0), b3, voffB); PG8_STAGE(PG8_SB(1, 1), b3 + hstep, voffB); PG8_STAGE(PG8_SA(1, 0), a3, voffA);
;             PG8_WAIT_V(8); PG8_WAIT_L(0); PG8_BAR; PG8_MMA(1, 0, At, B0); PG8_MMA(1, 1, At, B1); PG8_BAR; PG8_SCHED;
	s_add_i32 s4, 0, 0x18000
	v_add_u32_e32 v126, s4, v242
	s_add_i32 s5, 0, 0x1c000
	ds_read_b128 v[50:53], v126
	ds_read_b128 v[66:69], v126 offset:1024
	ds_read_b128 v[114:117], v126 offset:2048
	ds_read_b128 v[130:133], v126 offset:3072
	v_add_u32_e32 v126, s5, v242
	ds_read_b128 v[134:137], v126
	ds_read_b128 v[154:157], v126 offset:1024
	ds_read_b128 v[158:161], v126 offset:2048
	ds_read_b128 v[162:165], v126 offset:3072
	s_add_u32 s0, s12, 0x40000
	s_addc_u32 s1, s13, 0
	s_mov_b32 m0, s80
	ds_read_b128 v[126:129], v243 offset:32768
	ds_read_b128 v[166:169], v243 offset:33792
	ds_read_b128 v[170:173], v243 offset:34816
	ds_read_b128 v[174:177], v243 offset:35840
	ds_read_b128 v[178:181], v243 offset:36864
	ds_read_b128 v[182:185], v243 offset:37888
	ds_read_b128 v[186:189], v243 offset:38912
	ds_read_b128 v[190:193], v243 offset:39936
	global_load_lds_dwordx4 v210, s[0:1]
	s_mov_b32 m0, s81
	s_nop 0
	global_load_lds_dwordx4 v212, s[0:1]
	s_waitcnt vmcnt(8)
	s_waitcnt lgkmcnt(0)
	s_barrier
	s_setprio 1
	s_waitcnt lgkmcnt(0)
	v_mfma_i32_16x16x64_i8 v[150:153], v[50:53], v[126:129], v[150:153]
	v_mfma_i32_16x16x64_i8 v[146:149], v[114:117], v[126:129], v[146:149]
	v_mfma_i32_16x16x64_i8 v[118:121], v[50:53], v[170:173], v[118:121]
	v_mfma_i32_16x16x64_i8 v[110:113], v[114:117], v[170:173], v[110:113]
	v_mfma_i32_16x16x64_i8 v[54:57], v[50:53], v[178:181], v[54:57]
	v_mfma_i32_16x16x64_i8 v[30:33], v[114:117], v[178:181], v[30:33]
	v_mfma_i32_16x16x64_i8 v[94:97], v[50:53], v[186:189], v[94:97]
	v_mfma_i32_16x16x64_i8 v[58:61], v[114:117], v[186:189], v[58:61]
	v_mfma_i32_16x16x64_i8 v[150:153], v[66:69], v[166:169], v[150:153]
	v_mfma_i32_16x16x64_i8 v[146:149], v[130:133], v[166:169], v[146:149]
	v_mfma_i32_16x16x64_i8 v[118:121], v[66:69], v[174:177], v[118:121]
	v_mfma_i32_16x16x64_i8 v[110:113], v[130:133], v[174:177], v[110:113]
	v_mfma_i32_16x16x64_i8 v[54:57], v[66:69], v[182:185], v[54:57]
	v_mfma_i32_16x16x64_i8 v[30:33], v[130:133], v[182:185], v[30:33]
	v_mfma_i32_16x16x64_i8 v[94:97], v[66:69], v[190:193], v[94:97]
	v_mfma_i32_16x16x64_i8 v[58:61], v[130:133], v[190:193], v[58:61]
	s_setprio 0
	s_setprio 1
	v_mfma_i32_16x16x64_i8 v[142:145], v[134:137], v[126:129], v[142:145]
	v_mfma_i32_16x16x64_i8 v[126:129], v[158:161], v[126:129], v[138:141]
	v_mfma_i32_16x16x64_i8 v[102:105], v[134:137], v[170:173], v[102:105]
	v_mfma_i32_16x16x64_i8 v[98:101], v[158:161], v[170:173], v[98:101]
	v_mfma_i32_16x16x64_i8 v[42:45], v[134:137], v[178:181], v[42:45]
	v_mfma_i32_16x16x64_i8 v[26:29], v[158:161], v[178:181], v[26:29]
	v_mfma_i32_16x16x64_i8 v[78:81], v[134:137], v[186:189], v[78:81]
	v_mfma_i32_16x16x64_i8 v[62:65], v[158:161], v[186:189], v[62:65]
	v_mfma_i32_16x16x64_i8 v[142:145], v[154:157], v[166:169], v[142:145]
	v_mfma_i32_16x16x64_i8 v[138:141], v[162:165], v[166:169], v[126:129]
	v_mfma_i32_16x16x64_i8 v[102:105], v[154:157], v[174:177], v[102:105]
	v_mfma_i32_16x16x64_i8 v[98:101], v[162:165], v[174:177], v[98:101]
	v_mfma_i32_16x16x64_i8 v[42:45], v[154:157], v[182:185], v[42:45]
	v_mfma_i32_16x16x64_i8 v[26:29], v[162:165], v[182:185], v[26:29]
	v_mfma_i32_16x16x64_i8 v[78:81], v[154:157], v[190:193], v[78:81]
	v_mfma_i32_16x16x64_i8 v[62:65], v[162:165], v[190:193], v[62:65]
	s_setprio 0
	s_barrier
	s_add_i32 s0, s4, s69
	v_lshl_add_u64 v[126:127], v[198:199], 0, s[92:93]
	s_mov_b32 m0, s0
	ds_read_b128 v[166:169], v243 offset:49152
	ds_read_b128 v[170:173], v243 offset:50176
	ds_read_b128 v[174:177], v243 offset:51200
	ds_read_b128 v[178:181], v243 offset:52224
	ds_read_b128 v[182:185], v243 offset:53248
	ds_read_b128 v[186:189], v243 offset:54272
	ds_read_b128 v[190:193], v243 offset:55296
	ds_read_b128 v[194:197], v243 offset:56320
	global_load_lds_dwordx4 v[126:127], off
	s_add_i32 m0, s0, 0x2000
	s_add_u32 s0, s6, 0x40080
	v_lshl_add_u64 v[126:127], v[200:201], 0, s[92:93]
	s_addc_u32 s1, s7, 0
	s_add_i32 s4, s5, s69
	global_load_lds_dwordx4 v[126:127], off
	s_mov_b32 m0, s4
	s_nop 0
	global_load_lds_dwordx4 v0, s[0:1]
	s_add_i32 m0, s4, 0x2000
	s_nop 0
	global_load_lds_dwordx4 v214, s[0:1]
	v_lshl_add_u64 v[126:127], v[206:207], 0, s[92:93]
	s_mov_b32 m0, s84
	s_nop 0
	global_load_lds_dwordx4 v[126:127], off
	v_lshl_add_u64 v[126:127], v[220:221], 0, s[92:93]
	s_mov_b32 m0, s85
	s_nop 0
	global_load_lds_dwordx4 v[126:127], off
	s_waitcnt vmcnt(8)
	s_waitcnt lgkmcnt(0)
	s_barrier
	s_setprio 1
	s_waitcnt lgkmcnt(0)
	v_mfma_i32_16x16x64_i8 v[18:21], v[50:53], v[190:193], v[18:21]
	v_mfma_i32_16x16x64_i8 v[106:109], v[50:53], v[166:169], v[106:109]
	v_mfma_i32_16x16x64_i8 v[46:49], v[114:117], v[166:169], v[46:49]
	v_mfma_i32_16x16x64_i8 v[14:17], v[50:53], v[174:177], v[14:17]
	v_mfma_i32_16x16x64_i8 v[6:9], v[114:117], v[174:177], v[6:9]
	v_mfma_i32_16x16x64_i8 v[90:93], v[50:53], v[182:185], v[90:93]
	v_mfma_i32_16x16x64_i8 v[86:89], v[114:117], v[182:185], v[86:89]
	v_mfma_i32_16x16x64_i8 v[126:129], v[66:69], v[194:197], v[18:21]
	v_mfma_i32_16x16x64_i8 v[18:21], v[114:117], v[190:193], v[22:25]
	v_mfma_i32_16x16x64_i8 v[106:109], v[66:69], v[170:173], v[106:109]
	v_mfma_i32_16x16x64_i8 v[46:49], v[130:133], v[170:173], v[46:49]
	v_mfma_i32_16x16x64_i8 v[14:17], v[66:69], v[178:181], v[14:17]
	v_mfma_i32_16x16x64_i8 v[6:9], v[130:133], v[178:181], v[6:9]
	v_mfma_i32_16x16x64_i8 v[90:93], v[66:69], v[186:189], v[90:93]
	v_mfma_i32_16x16x64_i8 v[86:89], v[130:133], v[186:189], v[86:89]
	v_mfma_i32_16x16x64_i8 v[66:69], v[130:133], v[194:197], v[18:21]
	s_setprio 0
	s_setprio 1
	v_mfma_i32_16x16x64_i8 v[18:21], v[134:137], v[166:169], v[34:37]
	v_mfma_i32_16x16x64_i8 v[114:117], v[154:157], v[170:173], v[18:21]
	v_mfma_i32_16x16x64_i8 v[18:21], v[158:161], v[166:169], v[38:41]
	v_mfma_i32_16x16x64_i8 v[50:53], v[162:165], v[170:173], v[18:21]
	v_mfma_i32_16x16x64_i8 v[18:21], v[134:137], v[182:185], v[82:85]
	v_mfma_i32_16x16x64_i8 v[82:85], v[154:157], v[186:189], v[18:21]
	v_mfma_i32_16x16x64_i8 v[18:21], v[158:161], v[182:185], v[74:77]
	v_mfma_i32_16x16x64_i8 v[74:77], v[162:165], v[186:189], v[18:21]
	v_mfma_i32_16x16x64_i8 v[18:21], v[134:137], v[190:193], v[122:125]
	v_mfma_i32_16x16x64_i8 v[10:13], v[134:137], v[174:177], v[10:13]
	v_mfma_i32_16x16x64_i8 v[2:5], v[158:161], v[174:177], v[2:5]
	v_mfma_i32_16x16x64_i8 v[122:125], v[154:157], v[194:197], v[18:21]
	v_mfma_i32_16x16x64_i8 v[18:21], v[158:161], v[190:193], v[70:73]
	v_mfma_i32_16x16x64_i8 v[10:13], v[154:157], v[178:181], v[10:13]
	v_mfma_i32_16x16x64_i8 v[2:5], v[162:165], v[178:181], v[2:5]
	v_mfma_i32_16x16x64_i8 v[70:73], v[162:165], v[194:197], v[18:21]
	s_setprio 0
	s_barrier
	s_add_i32 vcc_lo, vcc_lo, 2
	s_add_u32 s96, s96, 0x100
	s_addc_u32 s97, s97, 0
	s_cmp_gt_u32 vcc_lo, 13
	s_mov_b64 s[0:1], s[8:9]
	s_cbranch_scc0 .LBB0_80
	s_branch .Lpeelx80
; #define PG8_STAGE(bufoff, gbase, voff) do { _Pragma("unroll") for (int _i = 0; _i < 2; ++_i) \
;         __builtin_amdgcn_global_load_lds((const unsigned*)((const char*)(gbase) + (voff)[_i]), (PG8_LAS unsigned*)(lds + (bufoff) + ldsw + _i * 8192), 16, 0, 0); } while (0)
; #define PG8_LDA(dst, b, h) do { _Pragma("unroll") for (int m = 0; m < 4; ++m) _Pragma("unroll") for (int k = 0; k < 2; ++k) dst[m][k] = *(const PG8_LAS bf16x8*)(lds + PG8_SA(b, h) + aoff + m * 2048 + k * 1024); } while (0)
; #define PG8_LDB(dst, b, h) do { _Pragma("unroll") for (int n = 0; n < 2; ++n) _Pragma("unroll") for (int k = 0; k < 2; ++k) dst[n][k] = *(const PG8_LAS bf16x8*)(lds + PG8_SB(b, h) + boff + n * 2048 + k * 1024); } while (0)
; #define PG8_MMA(ai, bj, At, Bt) do { __builtin_amdgcn_s_setprio(1); _Pragma("unroll") for (int m = 0; m < 4; ++m) _Pragma("unroll") for (int n = 0; n < 2; ++n) _Pragma("unroll") for (int k = 0; k < 2; ++k) \
;         acc[ai][bj][m][n] = mma16<Epi::I8>(Bt[n][k], At[m][k], acc[ai][bj][m][n]); __builtin_amdgcn_s_setprio(0); } while (0)
; #define PG8_WAIT_V(n) asm volatile("s_waitcnt vmcnt(" #n ")" ::: "memory")
; #define PG8_WAIT_L(n) asm volatile("s_waitcnt lgkmcnt(" #n ")" ::: "memory")
; #define PG8_BAR __builtin_amdgcn_s_barrier()
; #define PG8_SCHED __builtin_amdgcn_sched_barrier(0)
; template <class Epi, class Sched, bool ALIGN_EPI = false, bool SP2 = false>
; __device__ __forceinline__ void gemm_phase(PG8_LAS unsigned char* lds, const Gemm g, const Sched& S, const Epi& E) {
;     ...
;             PG8_LDB(B0, 0, 0); PG8_LDB(B1, 0, 1); PG8_SCHED; PG8_LDA(At, 0, 0); PG8_STAGE(PG8_SA(1, 1), a1 + hstep, voffA);
;             PG8_WAIT_V(8); PG8_WAIT_L(0); PG8_BAR; PG8_MMA(0, 0, At, B0); PG8_MMA(0, 1, At, B1); PG8_BAR; PG8_SCHED;
;             PG8_LDA(At, 0, 1); PG8_STAGE(PG8_SB(0, 0), b2, voffB); PG8_STAGE(PG8_SB(0, 1), b2 + hstep, voffB); PG8_STAGE(PG8_SA(0, 0), a2, voffA);
;             PG8_WAIT_V(8); PG8_WAIT_L(0); PG8_BAR; PG8_MMA(1, 0, At, B0); PG8_MMA(1, 1, At, B1); PG8_BAR; PG8_SCHED;
.LBB0_80:
	s_add_u32 s8, s0, 0x100
	s_addc_u32 s9, s1, 0
	s_add_i32 vcc_hi, 0, 0x10000
	s_cmp_eq_u32 vcc_lo, 12
	s_cselect_b32 s13, s66, s9
	s_cselect_b32 s12, s67, s8
	s_cselect_b32 s7, s82, s97
	s_cselect_b32 s6, s83, s96
	s_add_i32 s4, 0, 0x14000
	v_add_u32_e32 v38, vcc_hi, v242
	v_add_u32_e32 v158, s4, v242
	ds_read_b128 v[18:21], v38
	ds_read_b128 v[22:25], v38 offset:1024
	ds_read_b128 v[34:37], v38 offset:2048
	ds_read_b128 v[38:41], v38 offset:3072
	ds_read_b128 v[130:133], v158
	ds_read_b128 v[134:137], v158 offset:1024
	ds_read_b128 v[154:157], v158 offset:2048
	ds_read_b128 v[158:161], v158 offset:3072
	s_add_i32 m0, s11, 0xc000
	ds_read_b128 v[162:165], v243
	ds_read_b128 v[166:169], v243 offset:1024
	ds_read_b128 v[170:173], v243 offset:2048
	ds_read_b128 v[174:177], v243 offset:3072
	ds_read_b128 v[178:181], v243 offset:4096
	ds_read_b128 v[182:185], v243 offset:5120
	ds_read_b128 v[186:189], v243 offset:6144
	ds_read_b128 v[190:193], v243 offset:7168
	global_load_lds_dwordx4 v216, s[0:1]
	s_add_i32 m0, s11, 0xe000
	s_nop 0
	global_load_lds_dwordx4 v218, s[0:1]
	s_waitcnt vmcnt(8)
	s_waitcnt lgkmcnt(0)
	s_barrier
	s_setprio 1
	s_waitcnt lgkmcnt(0)
	v_mfma_i32_16x16x64_i8 v[150:153], v[18:21], v[162:165], v[150:153]
	v_mfma_i32_16x16x64_i8 v[146:149], v[34:37], v[162:165], v[146:149]
	v_mfma_i32_16x16x64_i8 v[118:121], v[18:21], v[170:173], v[118:121]
	v_mfma_i32_16x16x64_i8 v[110:113], v[34:37], v[170:173], v[110:113]
	v_mfma_i32_16x16x64_i8 v[54:57], v[18:21], v[178:181], v[54:57]
	v_mfma_i32_16x16x64_i8 v[30:33], v[34:37], v[178:181], v[30:33]
	v_mfma_i32_16x16x64_i8 v[94:97], v[18:21], v[186:189], v[94:97]
	v_mfma_i32_16x16x64_i8 v[58:61], v[34:37], v[186:189], v[58:61]
	v_mfma_i32_16x16x64_i8 v[150:153], v[22:25], v[166:169], v[150:153]
	v_mfma_i32_16x16x64_i8 v[146:149], v[38:41], v[166:169], v[146:149]
	v_mfma_i32_16x16x64_i8 v[118:121], v[22:25], v[174:177], v[118:121]
	v_mfma_i32_16x16x64_i8 v[110:113], v[38:41], v[174:177], v[110:113]
	v_mfma_i32_16x16x64_i8 v[54:57], v[22:25], v[182:185], v[54:57]
	v_mfma_i32_16x16x64_i8 v[30:33], v[38:41], v[182:185], v[30:33]
	v_mfma_i32_16x16x64_i8 v[94:97], v[22:25], v[190:193], v[94:97]
	v_mfma_i32_16x16x64_i8 v[58:61], v[38:41], v[190:193], v[58:61]
	s_setprio 0
	s_setprio 1
	v_mfma_i32_16x16x64_i8 v[142:145], v[130:133], v[162:165], v[142:145]
	v_mfma_i32_16x16x64_i8 v[138:141], v[154:157], v[162:165], v[138:141]
	v_mfma_i32_16x16x64_i8 v[102:105], v[130:133], v[170:173], v[102:105]
	v_mfma_i32_16x16x64_i8 v[98:101], v[154:157], v[170:173], v[98:101]
	v_mfma_i32_16x16x64_i8 v[42:45], v[130:133], v[178:181], v[42:45]
	v_mfma_i32_16x16x64_i8 v[26:29], v[154:157], v[178:181], v[26:29]
	v_mfma_i32_16x16x64_i8 v[78:81], v[130:133], v[186:189], v[78:81]
	v_mfma_i32_16x16x64_i8 v[62:65], v[154:157], v[186:189], v[62:65]
	v_mfma_i32_16x16x64_i8 v[142:145], v[134:137], v[166:169], v[142:145]
	v_mfma_i32_16x16x64_i8 v[138:141], v[158:161], v[166:169], v[138:141]
	v_mfma_i32_16x16x64_i8 v[102:105], v[134:137], v[174:177], v[102:105]
	v_mfma_i32_16x16x64_i8 v[98:101], v[158:161], v[174:177], v[98:101]
	v_mfma_i32_16x16x64_i8 v[42:45], v[134:137], v[182:185], v[42:45]
	v_mfma_i32_16x16x64_i8 v[26:29], v[158:161], v[182:185], v[26:29]
	v_mfma_i32_16x16x64_i8 v[78:81], v[134:137], v[190:193], v[78:81]
	v_mfma_i32_16x16x64_i8 v[62:65], v[158:161], v[190:193], v[62:65]
	s_setprio 0
	s_barrier
	s_add_i32 s0, vcc_hi, s69
	v_lshl_add_u64 v[198:199], s[6:7], 0, v[0:1]
	s_mov_b32 m0, s0
	ds_read_b128 v[162:165], v243 offset:16384
	ds_read_b128 v[166:169], v243 offset:17408
	ds_read_b128 v[170:173], v243 offset:18432
	ds_read_b128 v[174:177], v243 offset:19456
	ds_read_b128 v[178:181], v243 offset:20480
	ds_read_b128 v[182:185], v243 offset:21504
	ds_read_b128 v[186:189], v243 offset:22528
	ds_read_b128 v[190:193], v243 offset:23552
	global_load_lds_dwordx4 v[198:199], off
	s_add_i32 m0, s0, 0x2000
	s_add_u32 s0, s6, 0x40000
	v_lshl_add_u64 v[200:201], s[6:7], 0, v[214:215]
	s_addc_u32 s1, s7, 0
	s_add_i32 s4, s4, s69
	global_load_lds_dwordx4 v[200:201], off
	s_mov_b32 m0, s4
	v_lshl_add_u64 v[206:207], s[12:13], 0, v[210:211]
	global_load_lds_dwordx4 v0, s[0:1]
	s_add_i32 m0, s4, 0x2000
	v_lshl_add_u64 v[220:221], s[12:13], 0, v[212:213]
	global_load_lds_dwordx4 v214, s[0:1]
	s_mov_b32 m0, s11
	s_nop 0
	global_load_lds_dwordx4 v[206:207], off
	s_mov_b32 m0, s71
	s_nop 0
	global_load_lds_dwordx4 v[220:221], off
	s_waitcnt vmcnt(8)
	s_waitcnt lgkmcnt(0)
	s_barrier
	s_setprio 1
	s_waitcnt lgkmcnt(0)
	v_mfma_i32_16x16x64_i8 v[106:109], v[18:21], v[162:165], v[106:109]
	v_mfma_i32_16x16x64_i8 v[46:49], v[34:37], v[162:165], v[46:49]
	v_mfma_i32_16x16x64_i8 v[14:17], v[18:21], v[170:173], v[14:17]
	v_mfma_i32_16x16x64_i8 v[6:9], v[34:37], v[170:173], v[6:9]
	v_mfma_i32_16x16x64_i8 v[90:93], v[18:21], v[178:181], v[90:93]
	v_mfma_i32_16x16x64_i8 v[86:89], v[34:37], v[178:181], v[86:89]
	v_mfma_i32_16x16x64_i8 v[18:21], v[18:21], v[186:189], v[126:129]
	v_mfma_i32_16x16x64_i8 v[106:109], v[22:25], v[166:169], v[106:109]
	v_mfma_i32_16x16x64_i8 v[46:49], v[38:41], v[166:169], v[46:49]
	v_mfma_i32_16x16x64_i8 v[14:17], v[22:25], v[174:177], v[14:17]
	v_mfma_i32_16x16x64_i8 v[6:9], v[38:41], v[174:177], v[6:9]
	v_mfma_i32_16x16x64_i8 v[90:93], v[22:25], v[182:185], v[90:93]
	v_mfma_i32_16x16x64_i8 v[86:89], v[38:41], v[182:185], v[86:89]
	v_mfma_i32_16x16x64_i8 v[18:21], v[22:25], v[190:193], v[18:21]
	v_mfma_i32_16x16x64_i8 v[22:25], v[34:37], v[186:189], v[66:69]
	v_mfma_i32_16x16x64_i8 v[22:25], v[38:41], v[190:193], v[22:25]
	s_setprio 0
	s_setprio 1
	v_mfma_i32_16x16x64_i8 v[38:41], v[154:157], v[162:165], v[50:53]
	v_mfma_i32_16x16x64_i8 v[50:53], v[130:133], v[178:181], v[82:85]
	v_mfma_i32_16x16x64_i8 v[82:85], v[134:137], v[182:185], v[50:53]
	v_mfma_i32_16x16x64_i8 v[50:53], v[154:157], v[178:181], v[74:77]
	v_mfma_i32_16x16x64_i8 v[74:77], v[158:161], v[182:185], v[50:53]
	v_mfma_i32_16x16x64_i8 v[50:53], v[130:133], v[186:189], v[122:125]
	v_mfma_i32_16x16x64_i8 v[10:13], v[130:133], v[170:173], v[10:13]
	v_mfma_i32_16x16x64_i8 v[2:5], v[154:157], v[170:173], v[2:5]
	v_mfma_i32_16x16x64_i8 v[122:125], v[134:137], v[190:193], v[50:53]
	v_mfma_i32_16x16x64_i8 v[50:53], v[154:157], v[186:189], v[70:73]
	v_mfma_i32_16x16x64_i8 v[34:37], v[130:133], v[162:165], v[114:117]
	v_mfma_i32_16x16x64_i8 v[10:13], v[134:137], v[174:177], v[10:13]
	v_mfma_i32_16x16x64_i8 v[2:5], v[158:161], v[174:177], v[2:5]
	v_mfma_i32_16x16x64_i8 v[70:73], v[158:161], v[190:193], v[50:53]
	v_mfma_i32_16x16x64_i8 v[34:37], v[134:137], v[166:169], v[34:37]
	v_mfma_i32_16x16x64_i8 v[38:41], v[158:161], v[166:169], v[38:41]
	s_setprio 0
	s_barrier
; #define PG8_STAGE(bufoff, gbase, voff) do { _Pragma("unroll") for (int _i = 0; _i < 2; ++_i) \
;         __builtin_amdgcn_global_load_lds((const unsigned*)((const char*)(gbase) + (voff)[_i]), (PG8_LAS unsigned*)(lds + (bufoff) + ldsw + _i * 8192), 16, 0, 0); } while (0)
; #define PG8_LDA(dst, b, h) do { _Pragma("unroll") for (int m = 0; m < 4; ++m) _Pragma("unroll") for (int k = 0; k < 2; ++k) dst[m][k] = *(const PG8_LAS bf16x8*)(lds + PG8_SA(b, h) + aoff + m * 2048 + k * 1024); } while (0)
; #define PG8_LDB(dst, b, h) do { _Pragma("unroll") for (int n = 0; n < 2; ++n) _Pragma("unroll") for (int k = 0; k < 2; ++k) dst[n][k] = *(const PG8_LAS bf16x8*)(lds + PG8_SB(b, h) + boff + n * 2048 + k * 1024); } while (0)
; template <class Epi, class Sched, bool ALIGN_EPI = false, bool SP2 = false>
; __device__ __forceinline__ void gemm_phase(PG8_LAS unsigned char* lds, const Gemm g, const Sched& S, const Epi& E) {
;     ...
;         for (int t = 0; t < nt; t += 2) {
;             const bool last = (t == nt - 2);
;             const char* a1 = cA + (size_t)(t + 1) * kstep;
;             const char* a2 = last ? nA : cA + (size_t)(t + 2) * kstep; const char* b2 = last ? nB : cB + (size_t)(t + 2) * kstep;
;             const char* a3 = a2 + kstep; const char* b3 = b2 + kstep;
;             if (last && has_next) S.a_ready(nxt);
;             if constexpr (SP2) {
;             PG8_LDB(B0, 0, 0); PG8_LDB(B1, 0, 1); PG8_SCHED; PG8_LDA(At, 0, 0); PG8_STAGE(PG8_SA(1, 1), a1 + hstep, voffA);
;             PG8_WAIT_V(8); PG8_WAIT_L(0); PG8_BAR; PG8_MMA(0, 0, At, B0); PG8_MMA(0, 1, At, B1); PG8_BAR; PG8_SCHED;
;             PG8_LDA(At, 0, 1); PG8_STAGE(PG8_SB(0, 0), b2, voffB); PG8_STAGE(PG8_SB(0, 1), b2 + hstep, voffB); PG8_STAGE(PG8_SA(0, 0), a2, voffA);
;             PG8_WAIT_V(8); PG8_WAIT_L(0); PG8_BAR; PG8_MMA(1, 0, At, B0); PG8_MMA(1, 1, At, B1); PG8_BAR; PG8_SCHED;
;             PG8_LDB(B0, 1, 0); PG8_LDB(B1, 1, 1); PG8_SCHED; PG8_LDA(At, 1, 0); PG8_STAGE(PG8_SA(0, 1), a2 + hstep, voffA);
;             PG8_WAIT_V(8); PG8_WAIT_L(0); PG8_BAR; PG8_MMA(0, 0, At, B0); PG8_MMA(0, 1, At, B1); PG8_BAR; PG8_SCHED;
;             PG8_LDA(At, 1, 1); PG8_STAGE(PG8_SB(1, 0), b3, voffB); PG8_STAGE(PG8_SB(1, 1), b3 + hstep, voffB); PG8_STAGE(PG8_SA(1, 0), a3, voffA);
;             PG8_WAIT_V(8); PG8_WAIT_L(0); PG8_BAR; PG8_MMA(1, 0, At, B0); PG8_MMA(1, 1, At, B1); PG8_BAR; PG8_SCHED;
	s_add_i32 s4, 0, 0x18000
	v_add_u32_e32 v126, s4, v242
	s_add_i32 s5, 0, 0x1c000
	ds_read_b128 v[50:53], v126
	ds_read_b128 v[66:69], v126 offset:1024
	ds_read_b128 v[114:117], v126 offset:2048
	ds_read_b128 v[130:133], v126 offset:3072
	v_add_u32_e32 v126, s5, v242
	ds_read_b128 v[134:137], v126
	ds_read_b128 v[154:157], v126 offset:1024
	ds_read_b128 v[158:161], v126 offset:2048
	ds_read_b128 v[162:165], v126 offset:3072
	s_add_u32 s0, s12, 0x40000
	s_addc_u32 s1, s13, 0
	s_mov_b32 m0, s80
	ds_read_b128 v[126:129], v243 offset:32768
	ds_read_b128 v[166:169], v243 offset:33792
	ds_read_b128 v[170:173], v243 offset:34816
	ds_read_b128 v[174:177], v243 offset:35840
	ds_read_b128 v[178:181], v243 offset:36864
	ds_read_b128 v[182:185], v243 offset:37888
	ds_read_b128 v[186:189], v243 offset:38912
	ds_read_b128 v[190:193], v243 offset:39936
	global_load_lds_dwordx4 v210, s[0:1]
	s_mov_b32 m0, s81
	s_nop 0
	global_load_lds_dwordx4 v212, s[0:1]
	s_waitcnt vmcnt(8)
	s_waitcnt lgkmcnt(0)
	s_barrier
	s_setprio 1
	s_waitcnt lgkmcnt(0)
	v_mfma_i32_16x16x64_i8 v[150:153], v[50:53], v[126:129], v[150:153]
	v_mfma_i32_16x16x64_i8 v[146:149], v[114:117], v[126:129], v[146:149]
	v_mfma_i32_16x16x64_i8 v[118:121], v[50:53], v[170:173], v[118:121]
	v_mfma_i32_16x16x64_i8 v[110:113], v[114:117], v[170:173], v[110:113]
	v_mfma_i32_16x16x64_i8 v[54:57], v[50:53], v[178:181], v[54:57]
	v_mfma_i32_16x16x64_i8 v[30:33], v[114:117], v[178:181], v[30:33]
	v_mfma_i32_16x16x64_i8 v[94:97], v[50:53], v[186:189], v[94:97]
	v_mfma_i32_16x16x64_i8 v[58:61], v[114:117], v[186:189], v[58:61]
	v_mfma_i32_16x16x64_i8 v[150:153], v[66:69], v[166:169], v[150:153]
	v_mfma_i32_16x16x64_i8 v[146:149], v[130:133], v[166:169], v[146:149]
	v_mfma_i32_16x16x64_i8 v[118:121], v[66:69], v[174:177], v[118:121]
	v_mfma_i32_16x16x64_i8 v[110:113], v[130:133], v[174:177], v[110:113]
	v_mfma_i32_16x16x64_i8 v[54:57], v[66:69], v[182:185], v[54:57]
	v_mfma_i32_16x16x64_i8 v[30:33], v[130:133], v[182:185], v[30:33]
	v_mfma_i32_16x16x64_i8 v[94:97], v[66:69], v[190:193], v[94:97]
	v_mfma_i32_16x16x64_i8 v[58:61], v[130:133], v[190:193], v[58:61]
	s_setprio 0
	s_setprio 1
	v_mfma_i32_16x16x64_i8 v[142:145], v[134:137], v[126:129], v[142:145]
	v_mfma_i32_16x16x64_i8 v[126:129], v[158:161], v[126:129], v[138:141]
	v_mfma_i32_16x16x64_i8 v[102:105], v[134:137], v[170:173], v[102:105]
	v_mfma_i32_16x16x64_i8 v[98:101], v[158:161], v[170:173], v[98:101]
	v_mfma_i32_16x16x64_i8 v[42:45], v[134:137], v[178:181], v[42:45]
	v_mfma_i32_16x16x64_i8 v[26:29], v[158:161], v[178:181], v[26:29]
	v_mfma_i32_16x16x64_i8 v[78:81], v[134:137], v[186:189], v[78:81]
	v_mfma_i32_16x16x64_i8 v[62:65], v[158:161], v[186:189], v[62:65]
	v_mfma_i32_16x16x64_i8 v[142:145], v[154:157], v[166:169], v[142:145]
	v_mfma_i32_16x16x64_i8 v[138:141], v[162:165], v[166:169], v[126:129]
	v_mfma_i32_16x16x64_i8 v[102:105], v[154:157], v[174:177], v[102:105]
	v_mfma_i32_16x16x64_i8 v[98:101], v[162:165], v[174:177], v[98:101]
	v_mfma_i32_16x16x64_i8 v[42:45], v[154:157], v[182:185], v[42:45]
	v_mfma_i32_16x16x64_i8 v[26:29], v[162:165], v[182:185], v[26:29]
	v_mfma_i32_16x16x64_i8 v[78:81], v[154:157], v[190:193], v[78:81]
	v_mfma_i32_16x16x64_i8 v[62:65], v[162:165], v[190:193], v[62:65]
	s_setprio 0
	s_barrier
	s_add_i32 s0, s4, s69
	v_lshl_add_u64 v[126:127], v[198:199], 0, s[92:93]
	s_mov_b32 m0, s0
	ds_read_b128 v[166:169], v243 offset:49152
	ds_read_b128 v[170:173], v243 offset:50176
	ds_read_b128 v[174:177], v243 offset:51200
	ds_read_b128 v[178:181], v243 offset:52224
	ds_read_b128 v[182:185], v243 offset:53248
	ds_read_b128 v[186:189], v243 offset:54272
	ds_read_b128 v[190:193], v243 offset:55296
	ds_read_b128 v[194:197], v243 offset:56320
	global_load_lds_dwordx4 v[126:127], off
	s_add_i32 m0, s0, 0x2000
	s_add_u32 s0, s6, 0x40080
	v_lshl_add_u64 v[126:127], v[200:201], 0, s[92:93]
	s_addc_u32 s1, s7, 0
	s_add_i32 s4, s5, s69
	global_load_lds_dwordx4 v[126:127], off
	s_mov_b32 m0, s4
	s_nop 0
	global_load_lds_dwordx4 v0, s[0:1]
	s_add_i32 m0, s4, 0x2000
	s_nop 0
	global_load_lds_dwordx4 v214, s[0:1]
	v_lshl_add_u64 v[126:127], v[206:207], 0, s[92:93]
	s_mov_b32 m0, s84
	s_nop 0
	global_load_lds_dwordx4 v[126:127], off
	v_lshl_add_u64 v[126:127], v[220:221], 0, s[92:93]
	s_mov_b32 m0, s85
	s_nop 0
	global_load_lds_dwordx4 v[126:127], off
	s_waitcnt vmcnt(8)
	s_waitcnt lgkmcnt(0)
	s_barrier
	s_setprio 1
	s_waitcnt lgkmcnt(0)
	v_mfma_i32_16x16x64_i8 v[18:21], v[50:53], v[190:193], v[18:21]
	v_mfma_i32_16x16x64_i8 v[106:109], v[50:53], v[166:169], v[106:109]
	v_mfma_i32_16x16x64_i8 v[46:49], v[114:117], v[166:169], v[46:49]
	v_mfma_i32_16x16x64_i8 v[14:17], v[50:53], v[174:177], v[14:17]
	v_mfma_i32_16x16x64_i8 v[6:9], v[114:117], v[174:177], v[6:9]
	v_mfma_i32_16x16x64_i8 v[90:93], v[50:53], v[182:185], v[90:93]
	v_mfma_i32_16x16x64_i8 v[86:89], v[114:117], v[182:185], v[86:89]
	v_mfma_i32_16x16x64_i8 v[126:129], v[66:69], v[194:197], v[18:21]
	v_mfma_i32_16x16x64_i8 v[18:21], v[114:117], v[190:193], v[22:25]
	v_mfma_i32_16x16x64_i8 v[106:109], v[66:69], v[170:173], v[106:109]
	v_mfma_i32_16x16x64_i8 v[46:49], v[130:133], v[170:173], v[46:49]
	v_mfma_i32_16x16x64_i8 v[14:17], v[66:69], v[178:181], v[14:17]
	v_mfma_i32_16x16x64_i8 v[6:9], v[130:133], v[178:181], v[6:9]
	v_mfma_i32_16x16x64_i8 v[90:93], v[66:69], v[186:189], v[90:93]
	v_mfma_i32_16x16x64_i8 v[86:89], v[130:133], v[186:189], v[86:89]
	v_mfma_i32_16x16x64_i8 v[66:69], v[130:133], v[194:197], v[18:21]
	s_setprio 0
	s_setprio 1
	v_mfma_i32_16x16x64_i8 v[18:21], v[134:137], v[166:169], v[34:37]
	v_mfma_i32_16x16x64_i8 v[114:117], v[154:157], v[170:173], v[18:21]
	v_mfma_i32_16x16x64_i8 v[18:21], v[158:161], v[166:169], v[38:41]
	v_mfma_i32_16x16x64_i8 v[50:53], v[162:165], v[170:173], v[18:21]
	v_mfma_i32_16x16x64_i8 v[18:21], v[134:137], v[182:185], v[82:85]
	v_mfma_i32_16x16x64_i8 v[82:85], v[154:157], v[186:189], v[18:21]
	v_mfma_i32_16x16x64_i8 v[18:21], v[158:161], v[182:185], v[74:77]
	v_mfma_i32_16x16x64_i8 v[74:77], v[162:165], v[186:189], v[18:21]
	v_mfma_i32_16x16x64_i8 v[18:21], v[134:137], v[190:193], v[122:125]
	v_mfma_i32_16x16x64_i8 v[10:13], v[134:137], v[174:177], v[10:13]
	v_mfma_i32_16x16x64_i8 v[2:5], v[158:161], v[174:177], v[2:5]
	v_mfma_i32_16x16x64_i8 v[122:125], v[154:157], v[194:197], v[18:21]
	v_mfma_i32_16x16x64_i8 v[18:21], v[158:161], v[190:193], v[70:73]
	v_mfma_i32_16x16x64_i8 v[10:13], v[154:157], v[178:181], v[10:13]
	v_mfma_i32_16x16x64_i8 v[2:5], v[162:165], v[178:181], v[2:5]
	v_mfma_i32_16x16x64_i8 v[70:73], v[162:165], v[194:197], v[18:21]
	s_setprio 0
	s_barrier
	s_add_i32 vcc_lo, vcc_lo, 2
	s_add_u32 s96, s96, 0x100
	s_addc_u32 s97, s97, 0
	s_cmp_gt_u32 vcc_lo, 13
	s_mov_b64 s[0:1], s[8:9]
	s_cbranch_scc0 .LBB0_80
